# spatial phase: moved the compiler's vmcnt(0) from the pre-compute barrier to the first consumer of the prefetched next-item registers
# baseline (speedup 1.0000x reference)
.LBB0_59:
	v_lshlrev_b32_e32 v16, 16, v140
	v_fma_f32 v17, v32, v40, v138
	v_mul_f32_e32 v32, v17, v16
	v_and_b32_e32 v16, 0xffff0000, v140
	v_fma_f32 v17, v33, v41, v138
	v_mul_f32_e32 v33, v17, v16
	v_lshlrev_b32_e32 v16, 16, v141
	v_fma_f32 v17, v34, v42, v138
	v_mul_f32_e32 v34, v17, v16
	v_and_b32_e32 v16, 0xffff0000, v141
	v_fma_f32 v17, v35, v43, v138
	v_mul_f32_e32 v35, v17, v16
	v_mul_f32_e32 v16, v33, v33
	v_mul_f32_e32 v17, v34, v34
	v_fmac_f32_e32 v16, v32, v32
	v_fmac_f32_e32 v17, v35, v35
	v_add_f32_e32 v16, v16, v17
	v_lshlrev_b32_e32 v17, 16, v136
	v_fma_f32 v18, v36, v52, v138
	v_mul_f32_e32 v36, v18, v17
	v_and_b32_e32 v17, 0xffff0000, v136
	v_fma_f32 v18, v37, v53, v138
	v_mul_f32_e32 v37, v18, v17
	v_lshlrev_b32_e32 v17, 16, v137
	v_fma_f32 v18, v38, v54, v138
	v_mul_f32_e32 v38, v18, v17
	v_and_b32_e32 v17, 0xffff0000, v137
	v_fma_f32 v18, v39, v55, v138
	v_mul_f32_e32 v39, v18, v17
	v_mul_f32_e32 v17, v37, v37
	v_mul_f32_e32 v18, v38, v38
	v_fmac_f32_e32 v17, v36, v36
	v_fmac_f32_e32 v18, v39, v39
	v_add_f32_e32 v17, v17, v18
	v_add_f32_e32 v16, v16, v17
	v_lshlrev_b32_e32 v17, 16, v134
	v_fma_f32 v18, v44, v60, v138
	v_mul_f32_e32 v40, v18, v17
	v_and_b32_e32 v17, 0xffff0000, v134
	v_fma_f32 v18, v45, v61, v138
	v_mul_f32_e32 v41, v18, v17
	v_lshlrev_b32_e32 v17, 16, v135
	v_fma_f32 v18, v46, v62, v138
	v_mul_f32_e32 v42, v18, v17
	v_and_b32_e32 v17, 0xffff0000, v135
	v_fma_f32 v18, v47, v63, v138
	v_mul_f32_e32 v43, v18, v17
	v_mul_f32_e32 v17, v41, v41
	v_mul_f32_e32 v18, v42, v42
	v_fmac_f32_e32 v17, v40, v40
	v_fmac_f32_e32 v18, v43, v43
	v_add_f32_e32 v17, v17, v18
	v_add_f32_e32 v16, v16, v17
	v_lshlrev_b32_e32 v17, 16, v132
	v_fma_f32 v18, v48, v68, v138
	v_mul_f32_e32 v44, v18, v17
	v_and_b32_e32 v17, 0xffff0000, v132
	v_fma_f32 v18, v49, v69, v138
	v_mul_f32_e32 v45, v18, v17
	v_lshlrev_b32_e32 v17, 16, v133
	v_fma_f32 v18, v50, v70, v138
	v_mul_f32_e32 v46, v18, v17
	v_and_b32_e32 v17, 0xffff0000, v133
	v_fma_f32 v18, v51, v71, v138
	v_mul_f32_e32 v47, v18, v17
	v_mul_f32_e32 v17, v45, v45
	v_mul_f32_e32 v18, v46, v46
	v_fmac_f32_e32 v17, v44, v44
	v_fmac_f32_e32 v18, v47, v47
	v_add_f32_e32 v17, v17, v18
	v_add_f32_e32 v16, v16, v17
	v_lshlrev_b32_e32 v17, 16, v130
	v_fma_f32 v18, v56, v76, v138
	v_mul_f32_e32 v48, v18, v17
	v_and_b32_e32 v17, 0xffff0000, v130
	v_fma_f32 v18, v57, v77, v138
	v_mul_f32_e32 v49, v18, v17
	v_lshlrev_b32_e32 v17, 16, v131
	v_fma_f32 v18, v58, v78, v138
	v_mul_f32_e32 v50, v18, v17
	v_and_b32_e32 v17, 0xffff0000, v131
	v_fma_f32 v18, v59, v79, v138
	v_mul_f32_e32 v51, v18, v17
	v_mul_f32_e32 v17, v49, v49
	v_mul_f32_e32 v18, v50, v50
	v_fmac_f32_e32 v17, v48, v48
	v_fmac_f32_e32 v18, v51, v51
	v_add_f32_e32 v17, v17, v18
	v_add_f32_e32 v16, v16, v17
	v_lshlrev_b32_e32 v17, 16, v128
	v_fma_f32 v18, v64, v80, v138
	v_mul_f32_e32 v52, v18, v17
	v_and_b32_e32 v17, 0xffff0000, v128
	v_fma_f32 v18, v65, v81, v138
	v_mul_f32_e32 v53, v18, v17
	v_lshlrev_b32_e32 v17, 16, v129
	v_fma_f32 v18, v66, v82, v138
	v_mul_f32_e32 v54, v18, v17
	v_and_b32_e32 v17, 0xffff0000, v129
	v_fma_f32 v18, v67, v83, v138
	v_mul_f32_e32 v55, v18, v17
	v_mul_f32_e32 v17, v53, v53
	v_mul_f32_e32 v18, v54, v54
	v_fmac_f32_e32 v17, v52, v52
	v_fmac_f32_e32 v18, v55, v55
	v_add_f32_e32 v17, v17, v18
	v_add_f32_e32 v16, v16, v17
	v_lshlrev_b32_e32 v17, 16, v126
	s_waitcnt lgkmcnt(0)
	v_fma_f32 v18, v72, v28, v138
	v_mul_f32_e32 v28, v18, v17
	v_and_b32_e32 v17, 0xffff0000, v126
	v_fma_f32 v18, v73, v29, v138
	v_mul_f32_e32 v29, v18, v17
	v_lshlrev_b32_e32 v17, 16, v127
	v_fma_f32 v18, v74, v30, v138
	v_mul_f32_e32 v30, v18, v17
	v_and_b32_e32 v17, 0xffff0000, v127
	v_fma_f32 v18, v75, v31, v138
	v_mul_f32_e32 v31, v18, v17
	v_mul_f32_e32 v17, v29, v29
	v_mul_f32_e32 v18, v30, v30
	v_fmac_f32_e32 v17, v28, v28
	v_fmac_f32_e32 v18, v31, v31
	v_add_f32_e32 v17, v17, v18
	v_add_f32_e32 v21, v16, v17
	ds_read_b128 v[16:19], v89 offset:448
	v_and_b32_e32 v22, 0xffff0000, v124
	v_lshlrev_b32_e32 v23, 16, v125
	s_and_b32 s27, s33, 0xffffff80
	v_add_u32_e32 v20, s27, v102
	s_waitcnt lgkmcnt(0)
	v_pk_mul_f32 v[18:19], v[26:27], v[18:19]
	v_pk_mul_f32 v[24:25], v[24:25], v[16:17]
	v_lshl_add_u32 v27, s36, 2, v143
	v_pk_mov_b32 v[16:17], v[24:25], v[18:19] op_sel:[1,0]
	v_mov_b32_e32 v25, v19
	v_pk_add_f32 v[16:17], v[138:139], v[16:17] op_sel_hi:[0,1]
	v_pk_mul_f32 v[16:17], v[16:17], v[22:23]
	v_lshlrev_b32_e32 v22, 16, v124
	v_and_b32_e32 v23, 0xffff0000, v125
	v_pk_add_f32 v[18:19], v[138:139], v[24:25] op_sel_hi:[0,1]
	v_pk_mul_f32 v[18:19], v[18:19], v[22:23]
	v_pk_mul_f32 v[22:23], v[16:17], v[16:17]
	s_lshl_b32 s98, s36, 1
	v_pk_fma_f32 v[22:23], v[18:19], v[18:19], v[22:23]
	v_lshlrev_b32_e32 v144, 1, v85
	v_add_f32_e32 v22, v22, v23
	v_and_b32_e32 v23, 64, v214
	v_add_f32_e32 v21, v21, v22
	v_xor_b32_e32 v22, 16, v214
	v_add_u32_e32 v23, 64, v23
	v_cmp_lt_i32_e32 vcc, v22, v23
	s_xor_b32 s35, s35, 1
	s_add_i32 s33, s33, 32
	v_cndmask_b32_e32 v22, v214, v22, vcc
	v_lshlrev_b32_e32 v22, 2, v22
	ds_bpermute_b32 v22, v22, v21
	s_addk_i32 s34, 0x80
	s_waitcnt vmcnt(0)
	v_mov_b64_e32 v[140:141], v[120:121]
	v_mov_b64_e32 v[136:137], v[118:119]
	v_mov_b64_e32 v[134:135], v[116:117]
	s_waitcnt lgkmcnt(0)
	v_add_f32_e32 v21, v21, v22
	v_xor_b32_e32 v22, 32, v214
	v_cmp_lt_i32_e32 vcc, v22, v23
	v_mov_b64_e32 v[132:133], v[114:115]
	v_mov_b64_e32 v[130:131], v[112:113]
	v_cndmask_b32_e32 v22, v214, v22, vcc
	v_lshlrev_b32_e32 v22, 2, v22
	ds_bpermute_b32 v22, v22, v21
	v_mov_b64_e32 v[128:129], v[110:111]
	v_mov_b64_e32 v[126:127], v[108:109]
	v_mov_b64_e32 v[124:125], v[106:107]
	s_waitcnt lgkmcnt(0)
	v_add_f32_e32 v21, v21, v22
	v_fmamk_f32 v21, v21, 0x3c000000, v210
	v_cmp_gt_f32_e32 vcc, s89, v21
	v_mul_f32_e32 v22, 0x4b800000, v21
	s_nop 0
	v_cndmask_b32_e32 v21, v21, v22, vcc
	v_rsq_f32_e32 v21, v21
	s_nop 0
	v_mul_f32_e32 v22, 0x45800000, v21
	v_cndmask_b32_e32 v26, v21, v22, vcc
	ds_read_b128 v[22:25], v27
	v_mul_f32_e32 v32, v32, v26
	v_ashrrev_i32_e32 v21, 31, v20
	v_lshlrev_b64 v[20:21], 11, v[20:21]
	v_lshl_add_u64 v[20:21], s[44:45], 0, v[20:21]
	s_waitcnt lgkmcnt(0)
	v_mul_f32_e32 v22, v22, v32
	v_mul_f32_e32 v32, v33, v26
	v_mul_f32_e32 v23, v23, v32
	s_nop 0
	v_cvt_pk_bf16_f32 v22, v22, v23
	s_nop 1
	v_mul_f32_e32 v23, v34, v26
	v_mul_f32_e32 v23, v24, v23
	v_mul_f32_e32 v24, v35, v26
	v_lshl_add_u64 v[20:21], v[20:21], 0, s[98:99]
	v_mul_f32_e32 v24, v25, v24
	s_nop 0
	v_cvt_pk_bf16_f32 v23, v23, v24
	s_nop 1
	v_lshl_add_u64 v[24:25], v[20:21], 0, v[144:145]
	global_store_dwordx2 v[24:25], v[22:23], off
	ds_read_b128 v[20:23], v27 offset:64
	v_mul_f32_e32 v32, v36, v26
	v_mul_f32_e32 v28, v28, v26
	v_mul_f32_e32 v18, v18, v26
	v_mul_f32_e32 v16, v16, v26
	s_waitcnt lgkmcnt(0)
	v_mul_f32_e32 v20, v20, v32
	v_mul_f32_e32 v32, v37, v26
	v_mul_f32_e32 v21, v21, v32
	s_nop 0
	v_cvt_pk_bf16_f32 v20, v20, v21
	s_nop 1
	v_mul_f32_e32 v21, v38, v26
	v_mul_f32_e32 v21, v22, v21
	v_mul_f32_e32 v22, v39, v26
	v_mul_f32_e32 v22, v23, v22
	s_nop 0
	v_cvt_pk_bf16_f32 v21, v21, v22
	s_nop 1
	global_store_dwordx2 v[24:25], v[20:21], off offset:32
	ds_read_b128 v[20:23], v27 offset:128
	v_mul_f32_e32 v32, v40, v26
	v_mul_f32_e32 v17, v17, v26
	s_and_b64 vcc, exec, s[46:47]
	s_waitcnt lgkmcnt(0)
	v_mul_f32_e32 v20, v20, v32
	v_mul_f32_e32 v32, v41, v26
	v_mul_f32_e32 v21, v21, v32
	s_nop 0
	v_cvt_pk_bf16_f32 v20, v20, v21
	s_nop 1
	v_mul_f32_e32 v21, v42, v26
	v_mul_f32_e32 v21, v22, v21
	v_mul_f32_e32 v22, v43, v26
	v_mul_f32_e32 v22, v23, v22
	s_nop 0
	v_cvt_pk_bf16_f32 v21, v21, v22
	s_nop 1
	global_store_dwordx2 v[24:25], v[20:21], off offset:64
	ds_read_b128 v[20:23], v27 offset:192
	v_mul_f32_e32 v32, v44, v26
	s_waitcnt lgkmcnt(0)
	v_mul_f32_e32 v20, v20, v32
	v_mul_f32_e32 v32, v45, v26
	v_mul_f32_e32 v21, v21, v32
	s_nop 0
	v_cvt_pk_bf16_f32 v20, v20, v21
	s_nop 1
	v_mul_f32_e32 v21, v46, v26
	v_mul_f32_e32 v21, v22, v21
	v_mul_f32_e32 v22, v47, v26
	v_mul_f32_e32 v22, v23, v22
	s_nop 0
	v_cvt_pk_bf16_f32 v21, v21, v22
	s_nop 1
	global_store_dwordx2 v[24:25], v[20:21], off offset:96
	ds_read_b128 v[20:23], v27 offset:256
	v_mul_f32_e32 v32, v48, v26
	s_waitcnt lgkmcnt(0)
	v_mul_f32_e32 v20, v32, v20
	v_mul_f32_e32 v32, v49, v26
	v_mul_f32_e32 v21, v32, v21
	s_nop 0
	v_cvt_pk_bf16_f32 v20, v20, v21
	s_nop 1
	v_mul_f32_e32 v21, v50, v26
	v_mul_f32_e32 v21, v21, v22
	v_mul_f32_e32 v22, v51, v26
	v_mul_f32_e32 v22, v22, v23
	s_nop 0
	v_cvt_pk_bf16_f32 v21, v21, v22
	s_nop 1
	global_store_dwordx2 v[24:25], v[20:21], off offset:128
	ds_read_b128 v[20:23], v27 offset:320
	v_mul_f32_e32 v32, v52, v26
	s_waitcnt lgkmcnt(0)
	v_mul_f32_e32 v20, v32, v20
	v_mul_f32_e32 v32, v53, v26
	v_mul_f32_e32 v21, v32, v21
	s_nop 0
	v_cvt_pk_bf16_f32 v20, v20, v21
	s_nop 1
	v_mul_f32_e32 v21, v54, v26
	v_mul_f32_e32 v21, v21, v22
	v_mul_f32_e32 v22, v55, v26
	v_mul_f32_e32 v22, v22, v23
	s_nop 0
	v_cvt_pk_bf16_f32 v21, v21, v22
	s_nop 1
	global_store_dwordx2 v[24:25], v[20:21], off offset:160
	ds_read_b128 v[20:23], v27 offset:384
	v_mov_b64_e32 v[32:33], v[122:123]
	s_waitcnt lgkmcnt(0)
	v_mul_f32_e32 v20, v28, v20
	v_mul_f32_e32 v28, v29, v26
	v_mul_f32_e32 v21, v28, v21
	s_nop 0
	v_cvt_pk_bf16_f32 v20, v20, v21
	s_nop 1
	v_mul_f32_e32 v21, v30, v26
	v_mul_f32_e32 v21, v21, v22
	v_mul_f32_e32 v22, v31, v26
	v_mul_f32_e32 v22, v22, v23
	s_nop 0
	v_cvt_pk_bf16_f32 v21, v21, v22
	s_nop 1
	global_store_dwordx2 v[24:25], v[20:21], off offset:192
	ds_read_b128 v[20:23], v27 offset:448
	v_mov_b64_e32 v[30:31], v[6:7]
	v_mov_b64_e32 v[28:29], v[4:5]
	s_waitcnt lgkmcnt(0)
	v_mul_f32_e32 v18, v18, v20
	v_mul_f32_e32 v16, v16, v21
	s_nop 0
	v_cvt_pk_bf16_f32 v16, v18, v16
	s_nop 1
	v_mul_f32_e32 v17, v17, v22
	v_mul_f32_e32 v18, v19, v26
	v_mul_f32_e32 v18, v18, v23
	s_nop 0
	v_cvt_pk_bf16_f32 v17, v17, v18
	s_nop 1
	global_store_dwordx2 v[24:25], v[16:17], off offset:224
	s_waitcnt vmcnt(8)
	v_mov_b64_e32 v[26:27], v[2:3]
	v_mov_b64_e32 v[22:23], v[10:11]
	v_mov_b64_e32 v[18:19], v[14:15]
	v_mov_b64_e32 v[24:25], v[0:1]
	v_mov_b64_e32 v[20:21], v[8:9]
	v_mov_b64_e32 v[16:17], v[12:13]
	s_barrier
	s_cbranch_vccnz .LBB0_103

.LBB0_71:
	s_or_b64 exec, exec, s[50:51]
	s_waitcnt lgkmcnt(0)
	s_barrier
	ds_read_b64 v[32:33], v148
	v_lshlrev_b32_e32 v34, 16, v28
	v_and_b32_e32 v28, 0xffff0000, v28
	s_lshl_b32 s27, s35, 15
	s_add_i32 s27, s27, 0
	s_waitcnt lgkmcnt(0)
	v_mul_f32_e32 v32, v32, v34
	v_mul_f32_e32 v28, v33, v28
	s_nop 0
	v_cvt_pk_bf16_f32 v28, v32, v28
	s_nop 1
	ds_read_b64 v[32:33], v148 offset:8
	v_lshlrev_b32_e32 v34, 16, v29
	v_and_b32_e32 v29, 0xffff0000, v29
	v_add_u32_e32 v101, s27, v87
	v_add_u32_e32 v144, s27, v103
	s_waitcnt lgkmcnt(0)
	v_mul_f32_e32 v32, v32, v34
	v_mul_f32_e32 v29, v33, v29
	s_nop 0
	v_cvt_pk_bf16_f32 v29, v32, v29
	s_nop 1
	ds_read_b64 v[32:33], v148 offset:16
	v_lshlrev_b32_e32 v34, 16, v30
	v_and_b32_e32 v30, 0xffff0000, v30
	s_and_b64 vcc, exec, s[38:39]
	v_add_u32_e32 v93, s27, v139
	s_waitcnt lgkmcnt(0)
	v_mul_f32_e32 v32, v32, v34
	v_mul_f32_e32 v30, v33, v30
	s_nop 0
	v_cvt_pk_bf16_f32 v30, v32, v30
	s_nop 1
	ds_read_b64 v[32:33], v148 offset:24
	v_lshlrev_b32_e32 v34, 16, v31
	v_and_b32_e32 v31, 0xffff0000, v31
	s_waitcnt lgkmcnt(0)
	v_mul_f32_e32 v32, v32, v34
	v_mul_f32_e32 v31, v33, v31
	s_nop 0
	v_cvt_pk_bf16_f32 v31, v32, v31
	s_nop 1
	ds_read_b64 v[32:33], v148 offset:128
	v_lshlrev_b32_e32 v34, 16, v24
	v_and_b32_e32 v24, 0xffff0000, v24
	s_waitcnt lgkmcnt(0)
	v_mul_f32_e32 v32, v32, v34
	v_mul_f32_e32 v24, v33, v24
	s_nop 0
	v_cvt_pk_bf16_f32 v24, v32, v24
	s_nop 1
	ds_read_b64 v[32:33], v148 offset:136
	v_lshlrev_b32_e32 v34, 16, v25
	v_and_b32_e32 v25, 0xffff0000, v25
	s_waitcnt lgkmcnt(0)
	v_mul_f32_e32 v32, v32, v34
	v_mul_f32_e32 v25, v33, v25
	s_nop 0
	v_cvt_pk_bf16_f32 v25, v32, v25
	s_nop 1
	ds_read_b64 v[32:33], v148 offset:144
	v_lshlrev_b32_e32 v34, 16, v26
	v_and_b32_e32 v26, 0xffff0000, v26
	s_waitcnt lgkmcnt(0)
	v_mul_f32_e32 v32, v32, v34
	v_mul_f32_e32 v26, v33, v26
	s_nop 0
	v_cvt_pk_bf16_f32 v26, v32, v26
	s_nop 1
	ds_read_b64 v[32:33], v148 offset:152
	v_lshlrev_b32_e32 v34, 16, v27
	v_and_b32_e32 v27, 0xffff0000, v27
	s_waitcnt lgkmcnt(0)
	v_mul_f32_e32 v32, v32, v34
	v_mul_f32_e32 v27, v33, v27
	s_nop 0
	v_cvt_pk_bf16_f32 v27, v32, v27
	s_nop 1
	ds_read_b64 v[32:33], v148 offset:256
	v_lshlrev_b32_e32 v34, 16, v20
	v_and_b32_e32 v20, 0xffff0000, v20
	s_waitcnt lgkmcnt(0)
	v_mul_f32_e32 v32, v32, v34
	v_mul_f32_e32 v20, v33, v20
	s_nop 0
	v_cvt_pk_bf16_f32 v20, v32, v20
	s_nop 1
	ds_read_b64 v[32:33], v148 offset:264
	v_lshlrev_b32_e32 v34, 16, v21
	v_and_b32_e32 v21, 0xffff0000, v21
	s_waitcnt lgkmcnt(0)
	v_mul_f32_e32 v32, v32, v34
	v_mul_f32_e32 v21, v33, v21
	s_nop 0
	v_cvt_pk_bf16_f32 v21, v32, v21
	s_nop 1
	ds_read_b64 v[32:33], v148 offset:272
	v_lshlrev_b32_e32 v34, 16, v22
	v_and_b32_e32 v22, 0xffff0000, v22
	s_waitcnt lgkmcnt(0)
	v_mul_f32_e32 v32, v32, v34
	v_mul_f32_e32 v22, v33, v22
	s_nop 0
	v_cvt_pk_bf16_f32 v22, v32, v22
	s_nop 1
	ds_read_b64 v[32:33], v148 offset:280
	v_lshlrev_b32_e32 v34, 16, v23
	v_and_b32_e32 v23, 0xffff0000, v23
	s_waitcnt lgkmcnt(0)
	v_mul_f32_e32 v32, v32, v34
	v_mul_f32_e32 v23, v33, v23
	s_nop 0
	v_cvt_pk_bf16_f32 v23, v32, v23
	s_nop 1
	ds_read_b64 v[32:33], v148 offset:384
	v_lshlrev_b32_e32 v34, 16, v16
	v_and_b32_e32 v16, 0xffff0000, v16
	s_waitcnt lgkmcnt(0)
	v_mul_f32_e32 v32, v32, v34
	v_mul_f32_e32 v16, v33, v16
	s_nop 0
	v_cvt_pk_bf16_f32 v16, v32, v16
	s_nop 1
	ds_read_b64 v[32:33], v148 offset:392
	v_lshlrev_b32_e32 v34, 16, v17
	v_and_b32_e32 v17, 0xffff0000, v17
	s_waitcnt lgkmcnt(0)
	v_mul_f32_e32 v32, v32, v34
	v_mul_f32_e32 v17, v33, v17
	s_nop 0
	v_cvt_pk_bf16_f32 v17, v32, v17
	s_nop 1
	ds_read_b64 v[32:33], v148 offset:400
	v_lshlrev_b32_e32 v34, 16, v18
	v_and_b32_e32 v18, 0xffff0000, v18
	s_waitcnt lgkmcnt(0)
	v_mul_f32_e32 v32, v32, v34
	v_mul_f32_e32 v18, v33, v18
	s_nop 0
	v_cvt_pk_bf16_f32 v18, v32, v18
	s_nop 1
	ds_read_b64 v[32:33], v148 offset:408
	v_lshlrev_b32_e32 v34, 16, v19
	v_and_b32_e32 v19, 0xffff0000, v19
	s_waitcnt lgkmcnt(0)
	v_mul_f32_e32 v32, v32, v34
	v_mul_f32_e32 v19, v33, v19
	s_nop 0
	v_cvt_pk_bf16_f32 v19, v32, v19
	s_nop 1
	ds_read_b128 v[32:35], v101
	ds_read_b128 v[36:39], v144
	s_waitcnt lgkmcnt(1)
	v_mfma_f32_16x16x32_bf16 v[32:35], v[32:35], v[28:31], 0
	s_waitcnt lgkmcnt(0)
	v_mfma_f32_16x16x32_bf16 v[32:35], v[36:39], v[24:27], v[32:35]
	s_cbranch_vccnz .LBB0_73
	ds_read_b128 v[36:39], v93
	s_waitcnt lgkmcnt(0)
	v_mfma_f32_16x16x32_bf16 v[32:35], v[36:39], v[20:23], v[32:35]
